# prompt HGRN chains split 4-way over value columns (128 queue items, 2 compute waves each) to halve per-CU LDS traffic; plus norm-pass gain hoisting, prep load hoisting, chain DMA on idle waves, early
# speedup vs baseline: 1.0319x; 1.0023x over previous
; #define LAS __attribute__((address_space(3)))
; __global__ void __launch_bounds__(NTHR, 2) hybrid_fwd(Args args) {
;     ...
;     if (IN(6)) {
;         LAS int* qslot = (LAS int*)(lds + 147392);
;         constexpr int N_PCH = 64, N_ATT = 1088, N_SCH = 512, N_ALL = N_PCH + N_ATT + N_SCH;
;         for (;;) {
;             if (tid == 0) *qslot = (int)atomicAdd(ctl + CW_QUEUE, 1u);
;             __syncthreads();
;             const int it = *qslot;
;             __syncthreads();
;             if (it >= N_ALL) break;
;             if (it < N_PCH) { const int ch = it >> 1, b = ch >> 3, h = ch & 7;
;                 hgrn_chain(REC, nullptr, out + O_SP + (size_t)ch * 16384, MIX, b * 256, 256, h, it & 1, lds, wave, lane); }
;             else if (it < N_PCH + N_ATT) attn_item(Zb, args.in[I_CK], args.in[I_CV], BTAB, args.in[I_SINK], MIX, it - N_PCH, lds, tid, wave, lane);
;             else { const int si = it - N_PCH - N_ATT, sc = si >> 1, s = sc >> 3, h = sc & 7;
;                 hgrn_chain(REC, args.in[I_ST] + (size_t)sc * 16384, out + O_SS + (size_t)sc * 16384, MIX, 1024 + s * 2, 2, h, si & 1, lds, wave, lane); }
.LBB0_510:
	s_or_b64 exec, exec, s[6:7]
	s_waitcnt lgkmcnt(0)
	s_barrier
	s_waitcnt vmcnt(0)
	ds_read_b32 v0, v143
	s_movk_i32 s6, 0x6bf
	s_waitcnt lgkmcnt(0)
	s_barrier
	v_cmp_lt_i32_e32 vcc, s6, v0
	v_readfirstlane_b32 s79, v0
	s_mov_b64 s[6:7], -1
	s_cbranch_vccnz .LBB0_505
	s_cmpk_gt_i32 s79, 0x7f
	s_cbranch_scc0 .LBB0_594
	s_cmpk_gt_u32 s79, 0x4bf
	s_cbranch_scc0 .LBB0_574
	s_add_i32 s10, s79, 0xfffffb40
	s_lshr_b32 s76, s10, 1
	s_lshl_b64 s[6:7], s[76:77], 16
	v_readlane_b32 s8, v236, 31
	v_readlane_b32 s9, v236, 32
	s_add_u32 s8, s8, s6
	v_mov_b32_e32 v53, v128
	s_addc_u32 s9, s9, s7
	s_lshl_b32 s6, s79, 6
	v_lshrrev_b32_e32 v42, 2, v53
	s_and_b32 s6, s6, 64
	v_readlane_b32 s7, v236, 30
	v_and_b32_e32 v43, 12, v42
	v_readlane_b32 s14, v236, 46
	v_and_b32_e32 v52, 15, v53
	s_or_b32 s12, s6, s7
	v_readlane_b32 s15, v236, 47
	v_lshlrev_b32_e32 v0, 7, v43
	v_mov_b32_e32 v1, 0
	v_cmp_ne_u32_e64 s[6:7], 1, v142
	s_andn2_b64 vcc, exec, s[14:15]
	v_or3_b32 v32, v0, v52, s12
	v_mov_b32_e32 v0, 0
	s_cbranch_vccz .LBB0_650
	s_and_b64 vcc, exec, s[6:7]
	s_cbranch_vccz .LBB0_651

; __device__ __forceinline__ void attn_item(const bf16_t* Z, const float* ck, const float* cv, const float* btab, const float* sinks, bf16_t* MIX, int item, LAS unsigned char* lds, int tid, int wave, int lane) {
;     ...
;     const bool prompt = item < 1024;
;     int kvh, qrow0, krow0, kmin, sidx = 0;
;     if (prompt) { const int b = item >> 8, c = (item >> 1) & 127; kvh = item & 1; qrow0 = b * 8192 + c * 64; krow0 = qrow0 - 128; kmin = c == 0 ? 128 : (c == 1 ? 64 : 0); }
;     else { sidx = (item - 1024) >> 1; kvh = item & 1; qrow0 = MP + sidx * 64; krow0 = qrow0 - 128; kmin = 0; }
; __global__ void __launch_bounds__(NTHR, 2) hybrid_fwd(Args args) {
;     ...
;             else if (it < N_PCH + N_ATT) attn_item(Zb, args.in[I_CK], args.in[I_CV], BTAB, args.in[I_SINK], MIX, it - N_PCH, lds, tid, wave, lane);
.LBB0_574:
	s_and_b64 vcc, exec, s[6:7]
	s_cbranch_vccz .LBB0_593
	s_sub_i32 s10, s79, 0x80
	s_cmpk_gt_u32 s10, 0x3ff
	s_cselect_b64 s[8:9], -1, 0
	s_waitcnt vmcnt(0)
	v_mov_b32_e32 v8, v129
	v_mov_b32_e32 v125, v128
	s_mov_b64 s[6:7], -1
	s_and_b64 vcc, exec, s[8:9]
	s_cbranch_vccnz .LBB0_577
	s_bfe_u32 s6, s10, 0x70001
	s_lshl_b32 s7, s10, 5
	s_and_b32 s7, s7, 0x6000
	s_lshl_b32 s10, s6, 6
	s_or_b32 s20, s10, s7
	s_add_i32 s15, s20, 0xffffff80
	s_cmp_eq_u32 s6, 1
	s_cselect_b32 s7, 64, 0
	s_cmp_lg_u32 s6, 0
	s_cselect_b32 s66, s7, 0x80
	s_mov_b64 s[6:7], 0
.LBB0_577:
	s_mov_b32 s16, 0
	s_andn2_b64 vcc, exec, s[6:7]
	s_mov_b32 s17, 0
	s_cbranch_vccnz .LBB0_579
	s_add_i32 s6, s79, 0xfffffb80
	s_lshr_b32 s6, s6, 1
	s_lshl_b32 s7, s6, 6
	s_add_i32 s20, s7, 0x8000
	s_add_i32 s15, s7, 0x7f80
	s_lshl_b32 s17, s6, 7
	s_mov_b32 s66, 0

; #define CH_RAWBAR() do { asm volatile("s_waitcnt lgkmcnt(0)" ::: "memory"); __builtin_amdgcn_s_barrier(); asm volatile("" ::: "memory"); } while (0)
; #define CH_WAIT(EX) do { if (wave < 3) CH_WAITN(8 + (EX)); else if (wave == 3) CH_WAITN(6 + (EX)); else CH_WAITN(6); } while (0)
; __device__ __forceinline__ void hgrn_chain(const unsigned char* REC, const float* s0, float* sout, bf16_t* MIX,
;                                            int cidx0, int nchunks, int h, int vhalf, LAS unsigned char* lds, int wave, int lane) {
;     ...
;     const int c16 = lane & 15, g = lane >> 4, v0 = 64 * vhalf + 16 * (wave & 3);
;     const bool comp = wave < 4;
;     f32x4 S[8];
; #pragma unroll
;     for (int kb = 0; kb < 8; ++kb)
; #pragma unroll
;         for (int i = 0; i < 4; ++i) S[kb][i] = (s0 && comp) ? s0[(size_t)(16 * kb + 4 * g + i) * 128 + v0 + c16] : 0.f;
;     bf16_t* mo = MIX + (size_t)(cidx0 * 32 + c16) * D + 1024 + h * 128 + v0 + 4 * g;
;     const unsigned char* Rl = REC + ((size_t)cidx0 * 8 + h) * REC_STRIDE + lane * 16;
;     const unsigned char* Rlast = Rl + (size_t)(nchunks - 1) * 8 * REC_STRIDE;
;     asm volatile("s_waitcnt vmcnt(0)" ::: "memory");
;     const unsigned char* Ri = Rl;
; #pragma unroll
;     for (int cc = 0; cc < CH_NS - 1; ++cc) { ch_issue(Ri, lds + cc * CH_SLOT, wave); Ri = Ri < Rlast ? Ri + 8 * REC_STRIDE : Rlast; }
;     CH_WAIT(0);
;     CH_RAWBAR();
;     int slot = 0, islot = CH_NS - 1;
; __global__ void __launch_bounds__(NTHR, 2) hybrid_fwd(Args args) {
;     ...
;             if (it < N_PCH) { const int ch = it >> 1, b = ch >> 3, h = ch & 7;
;                 hgrn_chain(REC, nullptr, out + O_SP + (size_t)ch * 16384, MIX, b * 256, 256, h, it & 1, lds, wave, lane); }
.LBB0_595:
	s_lshl_b32 s6, s79, 3
	s_and_b32 s8, s6, 0xffffff00
	s_ashr_i32 s10, s79, 2
	s_ashr_i32 s9, s8, 31
	s_and_b32 s11, s10, 7
	s_lshl_b64 s[6:7], s[8:9], 3
	s_or_b32 s6, s6, s11
	s_mulk_i32 s7, 0x6a00
	s_mul_hi_u32 s9, s6, 0x6a00
	s_add_i32 s9, s9, s7
	s_mulk_i32 s6, 0x6a00
	s_waitcnt vmcnt(0)
	v_mov_b32_e32 v10, v128
	s_add_u32 s6, s94, s6
	s_addc_u32 s7, s95, s9
	v_lshlrev_b32_e32 v120, 4, v10
	v_lshl_add_u64 v[0:1], s[6:7], 0, v[120:121]
	s_waitcnt vmcnt(0)
	s_and_b64 vcc, exec, s[88:89]
	s_cbranch_vccnz .Lch_pro_done
	s_mul_i32 s12, s96, 7
	s_add_i32 s100, s12, 0xffff9000
	s_add_u32 s98, s6, s100
	s_addc_u32 s99, s7, 0
	s_movk_i32 s101, 0x1800
	s_cmp_eq_u32 s96, 0x1c00
	s_cselect_b32 s101, 0x1400, s101
	v_mov_b32_e32 v164, v120
	v_add_u32_e32 v165, 0x400, v120
	v_add_u32_e32 v166, 0x800, v120
	v_add_u32_e32 v167, 0xc00, v120
	v_add_u32_e32 v168, 0x1000, v120
	v_add_u32_e32 v169, 0x1400, v120
	v_add_u32_e32 v170, s101, v120
	s_mov_b64 s[12:13], s[98:99]
	s_mov_b32 s6, s100
	s_mov_b32 m0, s6
	s_nop 0
	global_load_lds_dwordx4 v164, s[12:13]
	s_add_i32 m0, s6, 0x400
	s_nop 0
	global_load_lds_dwordx4 v165, s[12:13]
	s_add_i32 m0, s6, 0x800
	s_nop 0
	global_load_lds_dwordx4 v166, s[12:13]
	s_add_i32 m0, s6, 0xc00
	s_nop 0
	global_load_lds_dwordx4 v167, s[12:13]
	s_add_i32 m0, s6, 0x1000
	s_nop 0
	global_load_lds_dwordx4 v168, s[12:13]
	s_add_i32 m0, s6, 0x1400
	s_nop 0
	global_load_lds_dwordx4 v169, s[12:13]
	s_add_i32 m0, s6, s101
	s_nop 0
	global_load_lds_dwordx4 v170, s[12:13]
	s_add_u32 s12, s98, 0x35000
	s_addc_u32 s13, s99, 0
	s_add_i32 s6, s100, 0x6c00
	s_mov_b32 m0, s6
	s_nop 0
	global_load_lds_dwordx4 v164, s[12:13]
	s_add_i32 m0, s6, 0x400
	s_nop 0
	global_load_lds_dwordx4 v165, s[12:13]
	s_add_i32 m0, s6, 0x800
	s_nop 0
	global_load_lds_dwordx4 v166, s[12:13]
	s_add_i32 m0, s6, 0xc00
	s_nop 0
	global_load_lds_dwordx4 v167, s[12:13]
	s_add_i32 m0, s6, 0x1000
	s_nop 0
	global_load_lds_dwordx4 v168, s[12:13]
	s_add_i32 m0, s6, 0x1400
	s_nop 0
	global_load_lds_dwordx4 v169, s[12:13]
	s_add_i32 m0, s6, s101
	s_nop 0
	global_load_lds_dwordx4 v170, s[12:13]
	s_add_u32 s12, s98, 0x6a000
	s_addc_u32 s13, s99, 0
	s_add_i32 s6, s100, 0xd800
	s_mov_b32 m0, s6
	s_nop 0
	global_load_lds_dwordx4 v164, s[12:13]
	s_add_i32 m0, s6, 0x400
	s_nop 0
	global_load_lds_dwordx4 v165, s[12:13]
	s_add_i32 m0, s6, 0x800
	s_nop 0
	global_load_lds_dwordx4 v166, s[12:13]
	s_add_i32 m0, s6, 0xc00
	s_nop 0
	global_load_lds_dwordx4 v167, s[12:13]
	s_add_i32 m0, s6, 0x1000
	s_nop 0
	global_load_lds_dwordx4 v168, s[12:13]
	s_add_i32 m0, s6, 0x1400
	s_nop 0
	global_load_lds_dwordx4 v169, s[12:13]
	s_add_i32 m0, s6, s101
	s_nop 0
	global_load_lds_dwordx4 v170, s[12:13]
	s_waitcnt vmcnt(14)
.Lch_pro_done:
.LBB0_603:
	s_mov_b64 s[12:13], 0x9f000
	s_lshl_b32 s9, s79, 5
	v_lshl_add_u64 v[44:45], v[0:1], 0, s[12:13]
	s_and_b32 s9, s9, 0x60
	v_readlane_b32 s12, v236, 30
	s_and_b32 s12, s12, 16
	s_or_b32 s14, s9, s12
	s_mov_b64 s[12:13], 0x34cb000
	v_and_b32_e32 v50, 15, v10
	v_lshl_add_u64 v[46:47], v[0:1], 0, s[12:13]
	v_lshlrev_b32_e32 v0, 6, v10
	v_or_b32_e32 v68, 0xc00, v0
	v_or_b32_e32 v73, 0x1c00, v0
	v_lshl_or_b32 v0, s8, 5, v50
	v_ashrrev_i32_e32 v1, 31, v0
	v_lshrrev_b32_e32 v2, 1, v10
	v_lshlrev_b64 v[0:1], 12, v[0:1]
	s_lshl_b32 s8, s11, 8
	v_and_b32_e32 v2, 24, v2
	v_lshrrev_b32_e32 v58, 2, v10
	v_or3_b32 v0, v0, s8, v2
	s_lshl_b32 s8, s14, 1
	v_readlane_b32 s9, v236, 44
	v_and_b32_e32 v59, 12, v58
	s_waitcnt lgkmcnt(0)
	s_barrier
	s_add_u32 s8, s9, s8
	v_readlane_b32 s9, v236, 45
	v_or_b32_e32 v57, 16, v59
	v_or_b32_e32 v56, 32, v59
	v_or_b32_e32 v55, 48, v59
	v_or_b32_e32 v54, 64, v59
	v_or_b32_e32 v53, 0x50, v59
	v_or_b32_e32 v52, 0x60, v59
	v_or_b32_e32 v51, 0x70, v59
	v_or_b32_e32 v60, s14, v50
	s_addc_u32 s9, s9, 0
	v_mov_b32_e32 v28, 0
	v_and_b32_e32 v61, 48, v10
	v_lshlrev_b32_e32 v62, 6, v60
	v_lshlrev_b32_e32 v63, 6, v50
	v_lshlrev_b32_e32 v64, 2, v59
	v_lshlrev_b32_e32 v65, 2, v57
	v_lshlrev_b32_e32 v66, 2, v56
	v_lshlrev_b32_e32 v67, 2, v55
	v_lshlrev_b32_e32 v69, 2, v54
	v_lshlrev_b32_e32 v70, 2, v53
	v_lshlrev_b32_e32 v71, 2, v52
	v_lshlrev_b32_e32 v72, 2, v51
	v_lshl_add_u64 v[48:49], s[8:9], 0, v[0:1]
	s_mov_b32 s15, 3
	s_mov_b32 s11, 0
	s_mov_b32 s16, 0
	v_mov_b32_e32 v29, v28
	v_mov_b32_e32 v30, v28
	v_mov_b32_e32 v31, v28
	v_mov_b32_e32 v24, v28
	v_mov_b32_e32 v25, v28
	v_mov_b32_e32 v26, v28
	v_mov_b32_e32 v27, v28
	v_mov_b32_e32 v20, v28
	v_mov_b32_e32 v21, v28
	v_mov_b32_e32 v22, v28
	v_mov_b32_e32 v23, v28
	v_mov_b32_e32 v16, v28
	v_mov_b32_e32 v17, v28
	v_mov_b32_e32 v18, v28
	v_mov_b32_e32 v19, v28
	v_mov_b32_e32 v12, v28
	v_mov_b32_e32 v13, v28
	v_mov_b32_e32 v14, v28
	v_mov_b32_e32 v15, v28
	v_mov_b32_e32 v8, v28
	v_mov_b32_e32 v9, v28
	v_mov_b32_e32 v10, v28
	v_mov_b32_e32 v11, v28
	v_mov_b32_e32 v4, v28
	v_mov_b32_e32 v5, v28
	v_mov_b32_e32 v6, v28
	v_mov_b32_e32 v7, v28
	v_mov_b32_e32 v0, v28
	v_mov_b32_e32 v1, v28
	v_mov_b32_e32 v2, v28
	v_mov_b32_e32 v3, v28
	s_branch .LBB0_605

; #define LAS __attribute__((address_space(3)))
; __device__ __forceinline__ void hgrn_chain(const unsigned char* REC, const float* s0, float* sout, bf16_t* MIX,
;                                            int cidx0, int nchunks, int h, int vhalf, LAS unsigned char* lds, int wave, int lane) {
;     ...
;         if (comp) {
;             bf16x8 QDf[2][4], KEf[8], ITf, Af[2]; f32x4 DEC[8];
; #pragma unroll
;             for (int kb = 0; kb < 8; ++kb) { DEC[kb] = *(const LAS f32x4*)(R + R_DEC + (16 * kb + 4 * g) * 4); KEf[kb] = *(const LAS bf16x8*)(R + R_KE + ((16 * kb + c16) * 32 + 8 * g) * 2); }
;             ITf = *(const LAS bf16x8*)(R + R_IT + ((v0 + c16) * 32 + 8 * g) * 2);
; #pragma unroll
;             for (int tb = 0; tb < 2; ++tb) {
;                 Af[tb] = *(const LAS bf16x8*)(R + R_A + ((16 * tb + c16) * 32 + 8 * g) * 2);
; #pragma unroll
;                 for (int kk = 0; kk < 4; ++kk) QDf[tb][kk] = *(const LAS bf16x8*)(R + R_QD + ((tb * 4 + kk) * 64 + lane) * 16);
;             }
;             bf16x8 Sb[4];
; #pragma unroll
;             for (int kk = 0; kk < 4; ++kk) {
;                 u32x4 sb; sb.x = cvt_pk_bf16(S[2 * kk][0], S[2 * kk][1]); sb.y = cvt_pk_bf16(S[2 * kk][2], S[2 * kk][3]);
;                 sb.z = cvt_pk_bf16(S[2 * kk + 1][0], S[2 * kk + 1][1]); sb.w = cvt_pk_bf16(S[2 * kk + 1][2], S[2 * kk + 1][3]);
;                 Sb[kk] = __builtin_bit_cast(bf16x8, sb);
;             }
; #pragma unroll
;             for (int kb = 0; kb < 8; ++kb) S[kb] = __builtin_amdgcn_mfma_f32_16x16x32_bf16(KEf[kb], ITf, S[kb] * DEC[kb], 0, 0, 0);
;             f32x4 o0 = {0.f, 0.f, 0.f, 0.f}, o1 = o0;
;             o0 = __builtin_amdgcn_mfma_f32_16x16x32_bf16(ITf, Af[0], o0, 0, 0, 0);
;             o1 = __builtin_amdgcn_mfma_f32_16x16x32_bf16(ITf, Af[1], o1, 0, 0, 0);
; #pragma unroll
;             for (int kk = 0; kk < 4; ++kk) { o0 = __builtin_amdgcn_mfma_f32_16x16x32_bf16(Sb[kk], QDf[0][kk], o0, 0, 0, 0); o1 = __builtin_amdgcn_mfma_f32_16x16x32_bf16(Sb[kk], QDf[1][kk], o1, 0, 0, 0); }
;             u32x2 w; w.x = cvt_pk_bf16(o0[0], o0[1]); w.y = cvt_pk_bf16(o0[2], o0[3]);
;             *(u32x2*)(mo + (size_t)c * 32 * D) = w;
;             w.x = cvt_pk_bf16(o1[0], o1[1]); w.y = cvt_pk_bf16(o1[2], o1[3]);
;             *(u32x2*)(mo + (size_t)c * 32 * D + (size_t)16 * D) = w;
;         }
.Lch_comp_new:
	v_readlane_b32 s12, v236, 35
	s_mov_b64 s[8:9], -1
	s_cmp_lt_u32 s12, 2
	s_cbranch_scc0 .LBB0_604
	s_mul_i32 s12, s16, 0x6c00
	v_add_u32_e32 v36, s12, v61
	v_add_u32_e32 v39, s12, v120
	v_add_u32_e32 v37, v36, v63
	v_add_u32_e32 v38, v36, v62
	ds_read_b128 v[32:35], v38 offset:16384
	ds_read_b128 v[164:167], v36 offset:26624
	ds_read_b128 v[196:199], v37 offset:8192
	ds_read_b128 v[168:171], v36 offset:26688
	ds_read_b128 v[200:203], v37 offset:9216
	ds_read_b128 v[172:175], v36 offset:26752
	ds_read_b128 v[204:207], v37 offset:10240
	ds_read_b128 v[176:179], v36 offset:26816
	ds_read_b128 v[208:211], v37 offset:11264
	ds_read_b128 v[180:183], v36 offset:26880
	ds_read_b128 v[212:215], v37 offset:12288
	ds_read_b128 v[184:187], v36 offset:26944
	ds_read_b128 v[216:219], v37 offset:13312
	ds_read_b128 v[188:191], v36 offset:27008
	ds_read_b128 v[220:223], v37 offset:14336
	s_mov_b64 s[8:9], 0
	v_cvt_pk_bf16_f32 v110, v28, v29
	v_cvt_pk_bf16_f32 v111, v30, v31
	v_cvt_pk_bf16_f32 v112, v24, v25
	v_cvt_pk_bf16_f32 v113, v26, v27
	v_cvt_pk_bf16_f32 v114, v20, v21
	v_cvt_pk_bf16_f32 v115, v22, v23
	v_cvt_pk_bf16_f32 v116, v16, v17
	v_cvt_pk_bf16_f32 v117, v18, v19
	v_cvt_pk_bf16_f32 v130, v12, v13
	v_cvt_pk_bf16_f32 v131, v14, v15
	v_cvt_pk_bf16_f32 v132, v8, v9
	v_cvt_pk_bf16_f32 v133, v10, v11
	v_cvt_pk_bf16_f32 v134, v4, v5
	v_cvt_pk_bf16_f32 v135, v6, v7
	v_cvt_pk_bf16_f32 v136, v0, v1
	v_cvt_pk_bf16_f32 v137, v2, v3
	s_waitcnt lgkmcnt(12)
	v_pk_mul_f32 v[28:29], v[28:29], v[164:165]
	v_pk_mul_f32 v[30:31], v[30:31], v[166:167]
	ds_read_b128 v[192:195], v36 offset:27072
	ds_read_b128 v[224:227], v37 offset:15360
	v_mfma_f32_16x16x32_bf16 v[28:31], v[196:199], v[32:35], v[28:31]
	s_waitcnt lgkmcnt(12)
	v_pk_mul_f32 v[24:25], v[24:25], v[168:169]
	v_pk_mul_f32 v[26:27], v[26:27], v[170:171]
	ds_read_b128 v[228:231], v37 offset:24576
	ds_read_b128 v[232:235], v37 offset:25600
	v_mfma_f32_16x16x32_bf16 v[24:27], v[200:203], v[32:35], v[24:27]
	s_waitcnt lgkmcnt(12)
	v_pk_mul_f32 v[20:21], v[20:21], v[172:173]
	v_pk_mul_f32 v[22:23], v[22:23], v[174:175]
	ds_read_b128 v[78:81], v39
	ds_read_b128 v[82:85], v39 offset:4096
	v_mfma_f32_16x16x32_bf16 v[20:23], v[204:207], v[32:35], v[20:23]
	s_waitcnt lgkmcnt(12)
	v_pk_mul_f32 v[16:17], v[16:17], v[176:177]
	v_pk_mul_f32 v[18:19], v[18:19], v[178:179]
	ds_read_b128 v[86:89], v39 offset:1024
	ds_read_b128 v[90:93], v39 offset:5120
	v_mfma_f32_16x16x32_bf16 v[16:19], v[208:211], v[32:35], v[16:19]
	s_waitcnt lgkmcnt(12)
	v_pk_mul_f32 v[12:13], v[12:13], v[180:181]
	v_pk_mul_f32 v[14:15], v[14:15], v[182:183]
	ds_read_b128 v[94:97], v39 offset:2048
	ds_read_b128 v[98:101], v39 offset:6144
	v_mfma_f32_16x16x32_bf16 v[12:15], v[212:215], v[32:35], v[12:15]
	s_waitcnt lgkmcnt(12)
	v_pk_mul_f32 v[8:9], v[8:9], v[184:185]
	v_pk_mul_f32 v[10:11], v[10:11], v[186:187]
	ds_read_b128 v[102:105], v39 offset:3072
	ds_read_b128 v[106:109], v39 offset:7168
	v_mfma_f32_16x16x32_bf16 v[8:11], v[216:219], v[32:35], v[8:11]
	s_waitcnt lgkmcnt(12)
	v_pk_mul_f32 v[4:5], v[4:5], v[188:189]
	v_pk_mul_f32 v[6:7], v[6:7], v[190:191]
	s_nop 1
	v_mfma_f32_16x16x32_bf16 v[4:7], v[220:223], v[32:35], v[4:7]
	s_waitcnt lgkmcnt(10)
	v_pk_mul_f32 v[0:1], v[0:1], v[192:193]
	v_pk_mul_f32 v[2:3], v[2:3], v[194:195]
	s_nop 1
	v_mfma_f32_16x16x32_bf16 v[0:3], v[224:227], v[32:35], v[0:3]
	s_waitcnt lgkmcnt(8)
	v_mfma_f32_16x16x32_bf16 v[138:141], v[32:35], v[228:231], 0
	v_mfma_f32_16x16x32_bf16 v[146:149], v[32:35], v[232:235], 0
	s_waitcnt lgkmcnt(7)
	v_mfma_f32_16x16x32_bf16 v[138:141], v[110:113], v[78:81], v[138:141]
	s_waitcnt lgkmcnt(6)
	v_mfma_f32_16x16x32_bf16 v[146:149], v[110:113], v[82:85], v[146:149]
	s_waitcnt lgkmcnt(5)
	v_mfma_f32_16x16x32_bf16 v[138:141], v[114:117], v[86:89], v[138:141]
	s_waitcnt lgkmcnt(4)
	v_mfma_f32_16x16x32_bf16 v[146:149], v[114:117], v[90:93], v[146:149]
	s_waitcnt lgkmcnt(3)
	v_mfma_f32_16x16x32_bf16 v[138:141], v[130:133], v[94:97], v[138:141]
	s_waitcnt lgkmcnt(2)
	v_mfma_f32_16x16x32_bf16 v[146:149], v[130:133], v[98:101], v[146:149]
	s_waitcnt lgkmcnt(1)
	v_mfma_f32_16x16x32_bf16 v[138:141], v[134:137], v[102:105], v[138:141]
	s_waitcnt lgkmcnt(0)
	v_mfma_f32_16x16x32_bf16 v[146:149], v[134:137], v[106:109], v[146:149]
	s_mov_b32 s12, 0xffff0000
	s_nop 6
	v_cvt_pk_bf16_f32 v36, v138, v139
	v_cvt_pk_bf16_f32 v37, v140, v141
	v_add_co_u32_e32 v38, vcc, s12, v48
	v_cvt_pk_bf16_f32 v40, v146, v147
	s_nop 0
	v_addc_co_u32_e32 v39, vcc, -1, v49, vcc
	v_cvt_pk_bf16_f32 v41, v148, v149
	global_store_dwordx2 v[38:39], v[36:37], off
	global_store_dwordx2 v[48:49], v[40:41], off
	s_branch .LBB0_604
